# P7 K-loop: A-operand LDS-DMA pieces issued first in each load segment (ahead of ds_reads and B pieces)
# speedup vs baseline: 1.0002x; 1.0002x over previous
; #define PG8_STAGE(bufoff, gbase, voff) do { _Pragma("unroll") for (int _i = 0; _i < 2; ++_i) \
;         __builtin_amdgcn_global_load_lds((const unsigned*)((const char*)(gbase) + (voff)[_i]), (PG8_LAS unsigned*)(lds + (bufoff) + ldsw + _i * 8192), 16, 0, 0); } while (0)
; #define PG8_LDA(dst, b, h) do { _Pragma("unroll") for (int m = 0; m < 4; ++m) _Pragma("unroll") for (int k = 0; k < 2; ++k) dst[m][k] = *(const PG8_LAS bf16x8*)(lds + PG8_SA(b, h) + aoff + m * 2048 + k * 1024); } while (0)
; #define PG8_LDB(dst, b, h) do { _Pragma("unroll") for (int n = 0; n < 2; ++n) _Pragma("unroll") for (int k = 0; k < 2; ++k) dst[n][k] = *(const PG8_LAS bf16x8*)(lds + PG8_SB(b, h) + boff + n * 2048 + k * 1024); } while (0)
; #define PG8_MMA(ai, bj, At, Bt) do { __builtin_amdgcn_s_setprio(1); _Pragma("unroll") for (int m = 0; m < 4; ++m) _Pragma("unroll") for (int n = 0; n < 2; ++n) _Pragma("unroll") for (int k = 0; k < 2; ++k) \
;         acc[ai][bj][m][n] = __builtin_amdgcn_mfma_f32_16x16x32_bf16(Bt[n][k], At[m][k], acc[ai][bj][m][n], 0, 0, 0); __builtin_amdgcn_s_setprio(0); } while (0)
; #define PG8_WAIT_V(n) asm volatile("s_waitcnt vmcnt(" #n ")" ::: "memory")
; #define PG8_WAIT_L(n) asm volatile("s_waitcnt lgkmcnt(" #n ")" ::: "memory")
; #define PG8_BAR __builtin_amdgcn_s_barrier()
; #define PG8_SCHED __builtin_amdgcn_sched_barrier(0)
;     ...
;             PG8_LDB(B0, 0, 0); PG8_LDB(B1, 0, 1); PG8_SCHED; PG8_LDA(At, 0, 0); PG8_STAGE(PG8_SA(1, 1), a1 + hstepA, voffA);
;             PG8_WAIT_V(8); PG8_WAIT_L(0); PG8_BAR; PG8_MMA(0, 0, At, B0); PG8_MMA(0, 1, At, B1); PG8_BAR; PG8_SCHED;
;             PG8_LDA(At, 0, 1); PG8_STAGE(PG8_SB(0, 0), b2, voffB); PG8_STAGE(PG8_SB(0, 1), b2 + hstepB, voffB); PG8_STAGE(PG8_SA(0, 0), a2, voffA);
;             PG8_WAIT_V(8); PG8_WAIT_L(0); PG8_BAR; PG8_MMA(1, 0, At, B0); PG8_MMA(1, 1, At, B1); PG8_BAR; PG8_SCHED;
.LBB0_1414:
	v_lshl_add_u64 v[160:161], s[26:27], 0, v[144:145]
	s_add_i32 m0, s8, 0xc000
	s_nop 0
	global_load_lds_dwordx4 v[160:161], off
	v_lshl_add_u64 v[160:161], s[26:27], 0, v[146:147]
	s_add_i32 m0, s8, 0xe000
	s_nop 0
	global_load_lds_dwordx4 v[160:161], off
	ds_read_b128 v[128:131], v163
	ds_read_b128 v[132:135], v163 offset:1024
	ds_read_b128 v[152:155], v163 offset:2048
	ds_read_b128 v[156:159], v163 offset:3072
	ds_read_b128 v[166:169], v164
	ds_read_b128 v[170:173], v164 offset:1024
	ds_read_b128 v[174:177], v164 offset:2048
	ds_read_b128 v[178:181], v164 offset:3072
	s_add_u32 s28, s26, 0xfff00080
	s_addc_u32 s29, s27, -1
	s_cmp_eq_u32 s52, 60
	s_cselect_b32 s35, s21, s29
	s_cselect_b32 s34, s48, s28
	s_cselect_b32 s29, s19, s51
	s_cselect_b32 s28, s49, s50
	ds_read_b128 v[182:185], v165
	ds_read_b128 v[186:189], v165 offset:1024
	ds_read_b128 v[190:193], v165 offset:2048
	ds_read_b128 v[194:197], v165 offset:3072
	ds_read_b128 v[198:201], v165 offset:4096
	ds_read_b128 v[202:205], v165 offset:5120
	ds_read_b128 v[206:209], v165 offset:6144
	ds_read_b128 v[210:213], v165 offset:7168
	s_waitcnt vmcnt(8)
	s_waitcnt lgkmcnt(0)
	s_barrier
	s_setprio 1
	s_waitcnt lgkmcnt(0)
	v_mfma_f32_16x16x32_bf16 v[124:127], v[128:131], v[182:185], v[124:127]
	v_mfma_f32_16x16x32_bf16 v[120:123], v[152:155], v[182:185], v[120:123]
	v_mfma_f32_16x16x32_bf16 v[108:111], v[128:131], v[190:193], v[108:111]
	v_mfma_f32_16x16x32_bf16 v[104:107], v[152:155], v[190:193], v[104:107]
	v_mfma_f32_16x16x32_bf16 v[92:95], v[128:131], v[198:201], v[92:95]
	v_mfma_f32_16x16x32_bf16 v[88:91], v[152:155], v[198:201], v[88:91]
	v_mfma_f32_16x16x32_bf16 v[76:79], v[128:131], v[206:209], v[76:79]
	v_mfma_f32_16x16x32_bf16 v[72:75], v[152:155], v[206:209], v[72:75]
	v_mfma_f32_16x16x32_bf16 v[124:127], v[132:135], v[186:189], v[124:127]
	v_mfma_f32_16x16x32_bf16 v[120:123], v[156:159], v[186:189], v[120:123]
	v_mfma_f32_16x16x32_bf16 v[108:111], v[132:135], v[194:197], v[108:111]
	v_mfma_f32_16x16x32_bf16 v[104:107], v[156:159], v[194:197], v[104:107]
	v_mfma_f32_16x16x32_bf16 v[92:95], v[132:135], v[202:205], v[92:95]
	v_mfma_f32_16x16x32_bf16 v[88:91], v[156:159], v[202:205], v[88:91]
	v_mfma_f32_16x16x32_bf16 v[76:79], v[132:135], v[210:213], v[76:79]
	v_mfma_f32_16x16x32_bf16 v[72:75], v[156:159], v[210:213], v[72:75]
	s_setprio 0
	s_setprio 1
	v_mfma_f32_16x16x32_bf16 v[116:119], v[166:169], v[182:185], v[116:119]
	v_mfma_f32_16x16x32_bf16 v[112:115], v[174:177], v[182:185], v[112:115]
	v_mfma_f32_16x16x32_bf16 v[100:103], v[166:169], v[190:193], v[100:103]
	v_mfma_f32_16x16x32_bf16 v[96:99], v[174:177], v[190:193], v[96:99]
	v_mfma_f32_16x16x32_bf16 v[84:87], v[166:169], v[198:201], v[84:87]
	v_mfma_f32_16x16x32_bf16 v[80:83], v[174:177], v[198:201], v[80:83]
	v_mfma_f32_16x16x32_bf16 v[68:71], v[166:169], v[206:209], v[68:71]
	v_mfma_f32_16x16x32_bf16 v[64:67], v[174:177], v[206:209], v[64:67]
	v_mfma_f32_16x16x32_bf16 v[116:119], v[170:173], v[186:189], v[116:119]
	v_mfma_f32_16x16x32_bf16 v[112:115], v[178:181], v[186:189], v[112:115]
	v_mfma_f32_16x16x32_bf16 v[100:103], v[170:173], v[194:197], v[100:103]
	v_mfma_f32_16x16x32_bf16 v[96:99], v[178:181], v[194:197], v[96:99]
	v_mfma_f32_16x16x32_bf16 v[84:87], v[170:173], v[202:205], v[84:87]
	v_mfma_f32_16x16x32_bf16 v[80:83], v[178:181], v[202:205], v[80:83]
	v_mfma_f32_16x16x32_bf16 v[68:71], v[170:173], v[210:213], v[68:71]
	v_mfma_f32_16x16x32_bf16 v[64:67], v[178:181], v[210:213], v[64:67]
	s_setprio 0
	s_barrier
	v_lshl_add_u64 v[216:217], s[34:35], 0, v[142:143]
	s_mov_b32 m0, s8
	s_nop 0
	global_load_lds_dwordx4 v[216:217], off
	v_lshl_add_u64 v[218:219], s[34:35], 0, v[138:139]
	s_mov_b32 m0, s13
	s_nop 0
	global_load_lds_dwordx4 v[218:219], off
	s_add_i32 s53, s46, s39
	v_lshl_add_u64 v[160:161], s[28:29], 0, v[140:141]
	s_mov_b32 m0, s53
	ds_read_b128 v[182:185], v165 offset:16384
	ds_read_b128 v[186:189], v165 offset:17408
	ds_read_b128 v[190:193], v165 offset:18432
	ds_read_b128 v[194:197], v165 offset:19456
	ds_read_b128 v[198:201], v165 offset:20480
	ds_read_b128 v[202:205], v165 offset:21504
	ds_read_b128 v[206:209], v165 offset:22528
	ds_read_b128 v[210:213], v165 offset:23552
	global_load_lds_dwordx4 v[160:161], off
	s_add_i32 m0, s53, 0x2000
	s_add_u32 s54, s28, 0x100000
	v_lshl_add_u64 v[214:215], s[28:29], 0, v[136:137]
	s_addc_u32 s55, s29, 0
	s_add_i32 s53, s47, s39
	global_load_lds_dwordx4 v[214:215], off
	v_lshl_add_u64 v[216:217], s[54:55], 0, v[140:141]
	s_mov_b32 m0, s53
	v_lshl_add_u64 v[218:219], s[34:35], 0, v[138:139]
	global_load_lds_dwordx4 v[216:217], off
	v_lshl_add_u64 v[216:217], s[54:55], 0, v[136:137]
	s_add_i32 m0, s53, 0x2000
	s_nop 0
	global_load_lds_dwordx4 v[216:217], off
	v_lshl_add_u64 v[216:217], s[34:35], 0, v[142:143]
	s_waitcnt vmcnt(8)
	s_waitcnt lgkmcnt(0)
	s_barrier
; #define PG8_STAGE(bufoff, gbase, voff) do { _Pragma("unroll") for (int _i = 0; _i < 2; ++_i) \
;         __builtin_amdgcn_global_load_lds((const unsigned*)((const char*)(gbase) + (voff)[_i]), (PG8_LAS unsigned*)(lds + (bufoff) + ldsw + _i * 8192), 16, 0, 0); } while (0)
; #define PG8_LDA(dst, b, h) do { _Pragma("unroll") for (int m = 0; m < 4; ++m) _Pragma("unroll") for (int k = 0; k < 2; ++k) dst[m][k] = *(const PG8_LAS bf16x8*)(lds + PG8_SA(b, h) + aoff + m * 2048 + k * 1024); } while (0)
; #define PG8_LDB(dst, b, h) do { _Pragma("unroll") for (int n = 0; n < 2; ++n) _Pragma("unroll") for (int k = 0; k < 2; ++k) dst[n][k] = *(const PG8_LAS bf16x8*)(lds + PG8_SB(b, h) + boff + n * 2048 + k * 1024); } while (0)
; #define PG8_MMA(ai, bj, At, Bt) do { __builtin_amdgcn_s_setprio(1); _Pragma("unroll") for (int m = 0; m < 4; ++m) _Pragma("unroll") for (int n = 0; n < 2; ++n) _Pragma("unroll") for (int k = 0; k < 2; ++k) \
;         acc[ai][bj][m][n] = __builtin_amdgcn_mfma_f32_16x16x32_bf16(Bt[n][k], At[m][k], acc[ai][bj][m][n], 0, 0, 0); __builtin_amdgcn_s_setprio(0); } while (0)
; #define PG8_WAIT_V(n) asm volatile("s_waitcnt vmcnt(" #n ")" ::: "memory")
; #define PG8_WAIT_L(n) asm volatile("s_waitcnt lgkmcnt(" #n ")" ::: "memory")
; #define PG8_BAR __builtin_amdgcn_s_barrier()
; #define PG8_SCHED __builtin_amdgcn_sched_barrier(0)
;     ...
;             PG8_WAIT_V(8); PG8_WAIT_L(0); PG8_BAR; PG8_MMA(1, 0, At, B0); PG8_MMA(1, 1, At, B1); PG8_BAR; PG8_SCHED;
;             PG8_LDB(B0, 1, 0); PG8_LDB(B1, 1, 1); PG8_SCHED; PG8_LDA(At, 1, 0); PG8_STAGE(PG8_SA(0, 1), a2 + hstepA, voffA);
;             PG8_WAIT_V(8); PG8_WAIT_L(0); PG8_BAR; PG8_MMA(0, 0, At, B0); PG8_MMA(0, 1, At, B1); PG8_BAR; PG8_SCHED;
	s_setprio 1
	s_waitcnt lgkmcnt(0)
	v_mfma_f32_16x16x32_bf16 v[60:63], v[128:131], v[182:185], v[60:63]
	v_mfma_f32_16x16x32_bf16 v[56:59], v[152:155], v[182:185], v[56:59]
	v_mfma_f32_16x16x32_bf16 v[48:51], v[128:131], v[190:193], v[48:51]
	v_mfma_f32_16x16x32_bf16 v[40:43], v[152:155], v[190:193], v[40:43]
	v_mfma_f32_16x16x32_bf16 v[32:35], v[128:131], v[198:201], v[32:35]
	v_mfma_f32_16x16x32_bf16 v[24:27], v[152:155], v[198:201], v[24:27]
	v_mfma_f32_16x16x32_bf16 v[16:19], v[128:131], v[206:209], v[16:19]
	v_mfma_f32_16x16x32_bf16 v[8:11], v[152:155], v[206:209], v[8:11]
	v_mfma_f32_16x16x32_bf16 v[60:63], v[132:135], v[186:189], v[60:63]
	v_mfma_f32_16x16x32_bf16 v[56:59], v[156:159], v[186:189], v[56:59]
	v_mfma_f32_16x16x32_bf16 v[48:51], v[132:135], v[194:197], v[48:51]
	v_mfma_f32_16x16x32_bf16 v[40:43], v[156:159], v[194:197], v[40:43]
	v_mfma_f32_16x16x32_bf16 v[32:35], v[132:135], v[202:205], v[32:35]
	v_mfma_f32_16x16x32_bf16 v[24:27], v[156:159], v[202:205], v[24:27]
	v_mfma_f32_16x16x32_bf16 v[16:19], v[132:135], v[210:213], v[16:19]
	v_mfma_f32_16x16x32_bf16 v[8:11], v[156:159], v[210:213], v[8:11]
	s_setprio 0
	s_setprio 1
	v_mfma_f32_16x16x32_bf16 v[52:55], v[166:169], v[182:185], v[52:55]
	v_mfma_f32_16x16x32_bf16 v[44:47], v[174:177], v[182:185], v[44:47]
	v_mfma_f32_16x16x32_bf16 v[36:39], v[166:169], v[190:193], v[36:39]
	v_mfma_f32_16x16x32_bf16 v[28:31], v[174:177], v[190:193], v[28:31]
	v_mfma_f32_16x16x32_bf16 v[20:23], v[166:169], v[198:201], v[20:23]
	v_mfma_f32_16x16x32_bf16 v[12:15], v[174:177], v[198:201], v[12:15]
	v_mfma_f32_16x16x32_bf16 v[4:7], v[166:169], v[206:209], v[4:7]
	v_mfma_f32_16x16x32_bf16 v[0:3], v[174:177], v[206:209], v[0:3]
	v_mfma_f32_16x16x32_bf16 v[52:55], v[170:173], v[186:189], v[52:55]
	v_mfma_f32_16x16x32_bf16 v[44:47], v[178:181], v[186:189], v[44:47]
	v_mfma_f32_16x16x32_bf16 v[36:39], v[170:173], v[194:197], v[36:39]
	v_mfma_f32_16x16x32_bf16 v[28:31], v[178:181], v[194:197], v[28:31]
	v_mfma_f32_16x16x32_bf16 v[20:23], v[170:173], v[202:205], v[20:23]
	v_mfma_f32_16x16x32_bf16 v[12:15], v[178:181], v[202:205], v[12:15]
	v_mfma_f32_16x16x32_bf16 v[4:7], v[170:173], v[210:213], v[4:7]
	v_mfma_f32_16x16x32_bf16 v[0:3], v[178:181], v[210:213], v[0:3]
	s_setprio 0
	s_barrier
	s_add_u32 s34, s34, 0x100000
	s_addc_u32 s35, s35, 0
	v_lshl_add_u64 v[220:221], s[34:35], 0, v[142:143]
	s_mov_b32 m0, s40
	s_nop 0
	global_load_lds_dwordx4 v[220:221], off
	v_lshl_add_u64 v[220:221], s[34:35], 0, v[138:139]
	s_mov_b32 m0, s41
	s_nop 0
	global_load_lds_dwordx4 v[220:221], off
	s_add_i32 s53, 0, 0x18000
	s_add_i32 s54, 0, 0x1c000
	v_add_u32_e32 v156, s53, v162
	v_add_u32_e32 v178, s54, v162
	ds_read_b128 v[128:131], v156
	ds_read_b128 v[132:135], v156 offset:1024
	ds_read_b128 v[152:155], v156 offset:2048
	ds_read_b128 v[156:159], v156 offset:3072
	ds_read_b128 v[166:169], v178
	ds_read_b128 v[170:173], v178 offset:1024
	ds_read_b128 v[174:177], v178 offset:2048
	ds_read_b128 v[178:181], v178 offset:3072
	ds_read_b128 v[182:185], v165 offset:32768
	ds_read_b128 v[186:189], v165 offset:33792
	ds_read_b128 v[190:193], v165 offset:34816
	ds_read_b128 v[194:197], v165 offset:35840
	ds_read_b128 v[198:201], v165 offset:36864
	ds_read_b128 v[202:205], v165 offset:37888
	ds_read_b128 v[206:209], v165 offset:38912
	ds_read_b128 v[210:213], v165 offset:39936
	s_waitcnt vmcnt(8)
	s_waitcnt lgkmcnt(0)
	s_barrier
	s_setprio 1
	s_waitcnt lgkmcnt(0)
	v_mfma_f32_16x16x32_bf16 v[124:127], v[128:131], v[182:185], v[124:127]
	v_mfma_f32_16x16x32_bf16 v[120:123], v[152:155], v[182:185], v[120:123]
	v_mfma_f32_16x16x32_bf16 v[108:111], v[128:131], v[190:193], v[108:111]
	v_mfma_f32_16x16x32_bf16 v[104:107], v[152:155], v[190:193], v[104:107]
	v_mfma_f32_16x16x32_bf16 v[92:95], v[128:131], v[198:201], v[92:95]
	v_mfma_f32_16x16x32_bf16 v[88:91], v[152:155], v[198:201], v[88:91]
	v_mfma_f32_16x16x32_bf16 v[76:79], v[128:131], v[206:209], v[76:79]
	v_mfma_f32_16x16x32_bf16 v[72:75], v[152:155], v[206:209], v[72:75]
	v_mfma_f32_16x16x32_bf16 v[124:127], v[132:135], v[186:189], v[124:127]
	v_mfma_f32_16x16x32_bf16 v[120:123], v[156:159], v[186:189], v[120:123]
	v_mfma_f32_16x16x32_bf16 v[108:111], v[132:135], v[194:197], v[108:111]
	v_mfma_f32_16x16x32_bf16 v[104:107], v[156:159], v[194:197], v[104:107]
	v_mfma_f32_16x16x32_bf16 v[92:95], v[132:135], v[202:205], v[92:95]
	v_mfma_f32_16x16x32_bf16 v[88:91], v[156:159], v[202:205], v[88:91]
	v_mfma_f32_16x16x32_bf16 v[76:79], v[132:135], v[210:213], v[76:79]
	v_mfma_f32_16x16x32_bf16 v[72:75], v[156:159], v[210:213], v[72:75]
	s_setprio 0
	s_setprio 1
	v_mfma_f32_16x16x32_bf16 v[116:119], v[166:169], v[182:185], v[116:119]
	v_mfma_f32_16x16x32_bf16 v[112:115], v[174:177], v[182:185], v[112:115]
	v_mfma_f32_16x16x32_bf16 v[100:103], v[166:169], v[190:193], v[100:103]
	v_mfma_f32_16x16x32_bf16 v[96:99], v[174:177], v[190:193], v[96:99]
	v_mfma_f32_16x16x32_bf16 v[84:87], v[166:169], v[198:201], v[84:87]
	v_mfma_f32_16x16x32_bf16 v[80:83], v[174:177], v[198:201], v[80:83]
	v_mfma_f32_16x16x32_bf16 v[68:71], v[166:169], v[206:209], v[68:71]
	v_mfma_f32_16x16x32_bf16 v[64:67], v[174:177], v[206:209], v[64:67]
	v_mfma_f32_16x16x32_bf16 v[116:119], v[170:173], v[186:189], v[116:119]
	v_mfma_f32_16x16x32_bf16 v[112:115], v[178:181], v[186:189], v[112:115]
	v_mfma_f32_16x16x32_bf16 v[100:103], v[170:173], v[194:197], v[100:103]
	v_mfma_f32_16x16x32_bf16 v[96:99], v[178:181], v[194:197], v[96:99]
	v_mfma_f32_16x16x32_bf16 v[84:87], v[170:173], v[202:205], v[84:87]
	v_mfma_f32_16x16x32_bf16 v[80:83], v[178:181], v[202:205], v[80:83]
	v_mfma_f32_16x16x32_bf16 v[68:71], v[170:173], v[210:213], v[68:71]
	v_mfma_f32_16x16x32_bf16 v[64:67], v[178:181], v[210:213], v[64:67]
	s_setprio 0
	s_barrier
; #define PG8_STAGE(bufoff, gbase, voff) do { _Pragma("unroll") for (int _i = 0; _i < 2; ++_i) \
;         __builtin_amdgcn_global_load_lds((const unsigned*)((const char*)(gbase) + (voff)[_i]), (PG8_LAS unsigned*)(lds + (bufoff) + ldsw + _i * 8192), 16, 0, 0); } while (0)
; #define PG8_LDA(dst, b, h) do { _Pragma("unroll") for (int m = 0; m < 4; ++m) _Pragma("unroll") for (int k = 0; k < 2; ++k) dst[m][k] = *(const PG8_LAS bf16x8*)(lds + PG8_SA(b, h) + aoff + m * 2048 + k * 1024); } while (0)
; #define PG8_MMA(ai, bj, At, Bt) do { __builtin_amdgcn_s_setprio(1); _Pragma("unroll") for (int m = 0; m < 4; ++m) _Pragma("unroll") for (int n = 0; n < 2; ++n) _Pragma("unroll") for (int k = 0; k < 2; ++k) \
;         acc[ai][bj][m][n] = __builtin_amdgcn_mfma_f32_16x16x32_bf16(Bt[n][k], At[m][k], acc[ai][bj][m][n], 0, 0, 0); __builtin_amdgcn_s_setprio(0); } while (0)
; #define PG8_WAIT_V(n) asm volatile("s_waitcnt vmcnt(" #n ")" ::: "memory")
; #define PG8_WAIT_L(n) asm volatile("s_waitcnt lgkmcnt(" #n ")" ::: "memory")
; #define PG8_BAR __builtin_amdgcn_s_barrier()
; #define PG8_SCHED __builtin_amdgcn_sched_barrier(0)
;     ...
;         for (int t = 0; t < nt; t += 2) {
;     ...
;             PG8_LDA(At, 1, 1); PG8_STAGE(PG8_SB(1, 0), b3, voffB); PG8_STAGE(PG8_SB(1, 1), b3 + hstepB, voffB); PG8_STAGE(PG8_SA(1, 0), a3, voffA);
;             PG8_WAIT_V(8); PG8_WAIT_L(0); PG8_BAR; PG8_MMA(1, 0, At, B0); PG8_MMA(1, 1, At, B1); PG8_BAR; PG8_SCHED;
	v_lshl_add_u64 v[220:221], v[216:217], 0, s[14:15]
	s_mov_b32 m0, s44
	s_nop 0
	global_load_lds_dwordx4 v[220:221], off
	v_lshl_add_u64 v[220:221], v[218:219], 0, s[14:15]
	s_mov_b32 m0, s45
	s_nop 0
	global_load_lds_dwordx4 v[220:221], off
	s_add_i32 s34, s53, s39
	v_lshl_add_u64 v[160:161], v[160:161], 0, s[14:15]
	s_mov_b32 m0, s34
	ds_read_b128 v[182:185], v165 offset:49152
	ds_read_b128 v[186:189], v165 offset:50176
	ds_read_b128 v[190:193], v165 offset:51200
	ds_read_b128 v[194:197], v165 offset:52224
	ds_read_b128 v[198:201], v165 offset:53248
	ds_read_b128 v[202:205], v165 offset:54272
	ds_read_b128 v[206:209], v165 offset:55296
	ds_read_b128 v[210:213], v165 offset:56320
	global_load_lds_dwordx4 v[160:161], off
	s_add_i32 m0, s34, 0x2000
	s_add_u32 s28, s28, 0x100080
	v_lshl_add_u64 v[160:161], v[214:215], 0, s[14:15]
	s_addc_u32 s29, s29, 0
	s_add_i32 s34, s54, s39
	global_load_lds_dwordx4 v[160:161], off
	v_lshl_add_u64 v[160:161], s[28:29], 0, v[140:141]
	s_mov_b32 m0, s34
	s_nop 0
	global_load_lds_dwordx4 v[160:161], off
	v_lshl_add_u64 v[160:161], s[28:29], 0, v[136:137]
	s_add_i32 m0, s34, 0x2000
	s_nop 0
	global_load_lds_dwordx4 v[160:161], off
	s_waitcnt vmcnt(8)
	s_waitcnt lgkmcnt(0)
	s_barrier
	s_setprio 1
	s_waitcnt lgkmcnt(0)
	v_mfma_f32_16x16x32_bf16 v[60:63], v[128:131], v[182:185], v[60:63]
	v_mfma_f32_16x16x32_bf16 v[56:59], v[152:155], v[182:185], v[56:59]
	v_mfma_f32_16x16x32_bf16 v[48:51], v[128:131], v[190:193], v[48:51]
	v_mfma_f32_16x16x32_bf16 v[40:43], v[152:155], v[190:193], v[40:43]
	v_mfma_f32_16x16x32_bf16 v[32:35], v[128:131], v[198:201], v[32:35]
	v_mfma_f32_16x16x32_bf16 v[24:27], v[152:155], v[198:201], v[24:27]
	v_mfma_f32_16x16x32_bf16 v[16:19], v[128:131], v[206:209], v[16:19]
	v_mfma_f32_16x16x32_bf16 v[8:11], v[152:155], v[206:209], v[8:11]
	v_mfma_f32_16x16x32_bf16 v[60:63], v[132:135], v[186:189], v[60:63]
	v_mfma_f32_16x16x32_bf16 v[56:59], v[156:159], v[186:189], v[56:59]
	v_mfma_f32_16x16x32_bf16 v[48:51], v[132:135], v[194:197], v[48:51]
	v_mfma_f32_16x16x32_bf16 v[40:43], v[156:159], v[194:197], v[40:43]
	v_mfma_f32_16x16x32_bf16 v[32:35], v[132:135], v[202:205], v[32:35]
	v_mfma_f32_16x16x32_bf16 v[24:27], v[156:159], v[202:205], v[24:27]
	v_mfma_f32_16x16x32_bf16 v[16:19], v[132:135], v[210:213], v[16:19]
	v_mfma_f32_16x16x32_bf16 v[8:11], v[156:159], v[210:213], v[8:11]
	s_setprio 0
	s_setprio 1
	v_mfma_f32_16x16x32_bf16 v[52:55], v[166:169], v[182:185], v[52:55]
	v_mfma_f32_16x16x32_bf16 v[44:47], v[174:177], v[182:185], v[44:47]
	v_mfma_f32_16x16x32_bf16 v[36:39], v[166:169], v[190:193], v[36:39]
	v_mfma_f32_16x16x32_bf16 v[28:31], v[174:177], v[190:193], v[28:31]
	v_mfma_f32_16x16x32_bf16 v[20:23], v[166:169], v[198:201], v[20:23]
	v_mfma_f32_16x16x32_bf16 v[12:15], v[174:177], v[198:201], v[12:15]
	v_mfma_f32_16x16x32_bf16 v[4:7], v[166:169], v[206:209], v[4:7]
	v_mfma_f32_16x16x32_bf16 v[0:3], v[174:177], v[206:209], v[0:3]
	v_mfma_f32_16x16x32_bf16 v[52:55], v[170:173], v[186:189], v[52:55]
	v_mfma_f32_16x16x32_bf16 v[44:47], v[178:181], v[186:189], v[44:47]
	v_mfma_f32_16x16x32_bf16 v[36:39], v[170:173], v[194:197], v[36:39]
	v_mfma_f32_16x16x32_bf16 v[28:31], v[178:181], v[194:197], v[28:31]
	v_mfma_f32_16x16x32_bf16 v[20:23], v[170:173], v[202:205], v[20:23]
	v_mfma_f32_16x16x32_bf16 v[12:15], v[178:181], v[202:205], v[12:15]
	v_mfma_f32_16x16x32_bf16 v[4:7], v[170:173], v[210:213], v[4:7]
	v_mfma_f32_16x16x32_bf16 v[0:3], v[178:181], v[210:213], v[0:3]
	s_setprio 0
	s_barrier
	s_add_i32 s52, s52, 2
	s_add_u32 s26, s26, 0x100
	s_addc_u32 s27, s27, 0
	s_add_u32 s50, s50, 0x100
	s_addc_u32 s51, s51, 0
	s_cmp_gt_u32 s52, 61
	s_cbranch_scc0 .LBB0_1414
	s_and_b64 vcc, exec, s[16:17]
	s_cbranch_vccz .LBB0_1417
	s_barrier
